# code placement: CL tile loop body shifted by 4 bytes
# baseline (speedup 1.0000x reference)
.LBB0_454:
	s_mul_i32 s4, s13, 0x2c00
	s_mul_hi_u32 s7, s12, 0x2c00
	s_add_i32 s7, s7, s4
	s_mul_i32 s4, s12, 0x2c00
	s_add_u32 s4, s38, s4
	s_addc_u32 s7, s39, s7
	s_add_u32 s8, s4, 0x1e74b200
	s_addc_u32 s9, s7, 0
	s_lshl_b32 s82, s5, 7
	s_add_u32 s4, s8, s82
	s_addc_u32 s7, s9, 0
	v_add_u32_e32 v146, s10, v170
	s_add_u32 s21, s4, 0x2400
	v_lshlrev_b32_e32 v2, 6, v146
	v_mov_b64_e32 v[0:1], s[8:9]
	s_addc_u32 s23, s7, 0
	v_lshrrev_b32_e32 v157, 6, v169
	v_and_b32_e32 v159, 15, v167
	v_mad_i64_i32 v[0:1], s[10:11], v2, s59, v[0:1]
	s_add_u32 s27, s4, 0x2600
	v_lshl_or_b32 v2, v157, 4, v159
	s_addc_u32 s28, s7, 0
	s_lshl_b32 s4, s5, 8
	v_mul_u32_u24_e32 v2, 0x1600, v2
	v_lshl_add_u64 v[0:1], v[0:1], 0, s[82:83]
	s_add_u32 s4, s8, s4
	v_bfe_u32 v45, v167, 4, 2
	v_lshlrev_b32_e32 v2, 1, v2
	v_mov_b32_e32 v3, v16
	s_addc_u32 s5, s9, 0
	v_lshlrev_b32_e32 v4, 4, v45
	v_mov_b32_e32 v5, v16
	v_lshl_add_u64 v[0:1], v[0:1], 0, v[2:3]
	s_add_u32 s24, s4, 0x2800
	v_lshl_add_u64 v[8:9], v[0:1], 0, v[4:5]
	s_addc_u32 s25, s5, 0
	s_mov_b64 s[0:1], 0x2000
	v_add_co_u32_e32 v10, vcc, s3, v8
	s_mov_b64 s[4:5], 0x2200
	v_lshl_add_u64 v[4:5], v[8:9], 0, s[0:1]
	v_addc_co_u32_e32 v11, vcc, 0, v9, vcc
	v_lshl_add_u64 v[12:13], v[8:9], 0, s[4:5]
	global_load_dwordx4 v[0:3], v[10:11], off
	s_nop 0
	global_load_dwordx4 v[4:7], v[4:5], off offset:64
	s_nop 0
	global_load_dwordx4 v[8:11], v[10:11], off offset:512
	s_nop 0
	global_load_dwordx4 v[18:21], v[12:13], off offset:64
	v_ashrrev_i32_e32 v12, 31, v167
	v_lshrrev_b32_e32 v12, 23, v12
	v_add_u32_e32 v12, v167, v12
	v_ashrrev_i32_e32 v48, 9, v12
	v_mul_i32_i24_e32 v12, 0x200, v48
	v_add_u32_e32 v30, 0x200, v167
	v_sub_u32_e32 v12, v167, v12
	v_ashrrev_i32_e32 v26, 31, v30
	v_ashrrev_i16_e32 v13, 15, v12
	v_lshrrev_b32_e32 v26, 23, v26
	v_lshrrev_b16_e32 v13, 13, v13
	v_add_u32_e32 v26, v30, v26
	v_add_u16_e32 v13, v12, v13
	v_ashrrev_i32_e32 v51, 9, v26
	v_ashrrev_i16_e32 v14, 3, v13
	v_and_b32_e32 v13, -8, v13
	v_mul_i32_i24_e32 v26, 0x200, v51
	v_sub_u16_e32 v12, v12, v13
	v_sub_u32_e32 v26, v30, v26
	v_bfe_i32 v50, v12, 0, 16
	v_add_u32_e32 v12, 0x1ff, v167
	s_movk_i32 s4, 0x3ff
	v_ashrrev_i16_e32 v27, 15, v26
	v_bfe_i32 v49, v14, 0, 16
	v_cmp_gt_u32_e64 s[4:5], s4, v12
	v_mov_b32_e32 v22, s28
	v_mov_b32_e32 v23, s23
	v_mov_b32_e32 v24, s27
	v_mov_b32_e32 v25, s21
	v_lshlrev_b32_e32 v148, 3, v50
	v_lshrrev_b16_e32 v27, 13, v27
	v_cndmask_b32_e64 v35, v22, v23, s[4:5]
	v_cndmask_b32_e64 v34, v24, v25, s[4:5]
	v_mul_hi_i32_i24_e32 v13, 0x2c00, v49
	v_mul_i32_i24_e32 v12, 0x2c00, v49
	v_ashrrev_i32_e32 v149, 31, v148
	v_add_u16_e32 v27, v26, v27
	v_lshl_add_u64 v[12:13], v[34:35], 0, v[12:13]
	v_lshlrev_b64 v[36:37], 1, v[148:149]
	v_ashrrev_i16_e32 v28, 3, v27
	v_and_b32_e32 v27, -8, v27
	v_lshl_add_u64 v[12:13], v[12:13], 0, v[36:37]
	v_sub_u16_e32 v26, v26, v27
	s_add_i32 s29, s6, s26
	global_load_dwordx4 v[12:15], v[12:13], off
	v_bfe_i32 v53, v26, 0, 16
	s_movk_i32 s6, 0xfc00
	v_bfe_i32 v52, v28, 0, 16
	v_cmp_lt_u32_e64 s[6:7], s6, v167
	v_lshlrev_b32_e32 v152, 3, v53
	v_ashrrev_i32_e32 v153, 31, v152
	v_cndmask_b32_e64 v39, v22, v23, s[6:7]
	v_cndmask_b32_e64 v38, v24, v25, s[6:7]
	v_mul_hi_i32_i24_e32 v23, 0x2c00, v52
	v_mul_i32_i24_e32 v22, 0x2c00, v52
	v_lshl_add_u64 v[22:23], v[38:39], 0, v[22:23]
	v_lshlrev_b64 v[40:41], 1, v[152:153]
	v_lshl_add_u64 v[22:23], v[22:23], 0, v[40:41]
	v_lshlrev_b32_e32 v28, 3, v167
	global_load_dwordx4 v[22:25], v[22:23], off
	v_ashrrev_i32_e32 v54, 4, v167
	v_mov_b64_e32 v[42:43], s[24:25]
	v_and_b32_e32 v44, 0x78, v28
	v_mad_i64_i32 v[26:27], s[8:9], v54, s59, v[42:43]
	v_lshlrev_b32_e32 v46, 1, v44
	v_mov_b32_e32 v47, v16
	v_ashrrev_i32_e32 v55, 4, v30
	v_lshl_add_u64 v[26:27], v[26:27], 0, v[46:47]
	v_mad_i64_i32 v[30:31], s[8:9], v55, s59, v[42:43]
	global_load_dwordx4 v[26:29], v[26:27], off
	v_lshl_add_u64 v[30:31], v[30:31], 0, v[46:47]
	global_load_dwordx4 v[30:33], v[30:31], off
	v_lshlrev_b32_e32 v48, 13, v48
	v_lshl_add_u32 v147, v49, 7, v48
	v_lshrrev_b32_e32 v48, 1, v49
	v_bitop3_b32 v48, v48, v50, 7 bitop3:0x6c
	v_lshlrev_b32_e32 v163, 4, v48
	v_add3_u32 v48, 0, v147, v163
	v_mul_lo_u32 v170, v54, s92
	v_mul_lo_u32 v172, v55, s92
	v_lshrrev_b32_e32 v17, 4, v167
	v_lshlrev_b32_e32 v160, 2, v45
	v_lshlrev_b32_e32 v154, 1, v44
	s_lshl_b32 s98, s20, 1
	s_lshl_b32 s99, s22, 1
	v_lshlrev_b32_e32 v252, 1, v148
	v_lshlrev_b32_e32 v253, 1, v152
	v_mad_u32_u24 v214, v49, s59, v252
	v_mad_u32_u24 v183, v52, s59, v253
	v_mad_u32_u24 v182, v54, s59, v154
	v_mad_u32_u24 v181, v55, s59, v154
	v_mad_u32_u24 v148, v49, s98, v252
	v_mad_u32_u24 v152, v52, s98, v253
	v_mad_u32_u24 v149, v54, s99, v154
	v_mad_u32_u24 v153, v55, s99, v154
	v_lshlrev_b32_e32 v178, 7, v159
	v_mov_b32_e32 v216, 0
	v_mov_b32_e32 v155, 0xf149f2ca
	v_mov_b32_e32 v217, 0xf149f2ca
	v_mov_b32_e32 v215, 0
	s_waitcnt vmcnt(0)
	ds_write_b128 v48, v[12:15]
	v_lshlrev_b32_e32 v12, 13, v51
	v_lshl_add_u32 v164, v52, 7, v12
	v_lshrrev_b32_e32 v12, 1, v52
	v_bitop3_b32 v12, v12, v53, 7 bitop3:0x6c
	v_lshlrev_b32_e32 v165, 4, v12
	v_add3_u32 v12, 0, v164, v165
	v_lshlrev_b32_e32 v14, 3, v169
	v_and_b32_e32 v15, 64, v191
	v_and_b32_e32 v169, 24, v14
	v_xor_b32_e32 v14, 16, v191
	v_add_u32_e32 v15, 64, v15
	v_cmp_lt_i32_e32 vcc, v14, v15
	ds_write_b128 v12, v[22:25]
	v_lshlrev_b32_e32 v12, 4, v167
	v_and_b32_e32 v171, 0xf0, v12
	v_add3_u32 v12, 0, v170, v171
	v_cndmask_b32_e32 v14, v191, v14, vcc
	v_lshlrev_b32_e32 v161, 2, v14
	v_xor_b32_e32 v14, 32, v191
	v_cmp_lt_i32_e32 vcc, v14, v15
	v_mov_b32_e32 v15, v16
	ds_write_b128 v12, v[26:29] offset:16384
	v_add3_u32 v12, 0, v172, v171
	ds_write_b128 v12, v[30:33] offset:16384
	v_add_u32_e32 v12, 64, v49
	v_mad_u64_u32 v[12:13], s[8:9], v12, s59, v[34:35]
	v_lshl_add_u64 v[12:13], v[12:13], 0, v[36:37]
	s_waitcnt lgkmcnt(0)
	s_barrier
	global_load_dwordx4 v[82:85], v[12:13], off
	v_add_u32_e32 v12, 64, v52
	v_mad_u64_u32 v[12:13], s[8:9], v12, s59, v[38:39]
	v_lshl_add_u64 v[12:13], v[12:13], 0, v[40:41]
	global_load_dwordx4 v[86:89], v[12:13], off
	v_add_u32_e32 v12, 64, v54
	v_mad_i64_i32 v[12:13], s[8:9], v12, s59, v[42:43]
	v_lshl_add_u64 v[12:13], v[12:13], 0, v[46:47]
	global_load_dwordx4 v[90:93], v[12:13], off
	v_add_u32_e32 v12, 64, v55
	v_mad_i64_i32 v[12:13], s[8:9], v12, s59, v[42:43]
	v_lshl_add_u64 v[12:13], v[12:13], 0, v[46:47]
	global_load_dwordx4 v[94:97], v[12:13], off
	v_bfe_u32 v12, v167, 1, 3
	v_cndmask_b32_e32 v14, v191, v14, vcc
	v_bfe_u32 v13, v167, 2, 2
	v_lshlrev_b32_e32 v162, 2, v14
	v_bitop3_b32 v14, v17, v12, 3 bitop3:0x6c
	v_bitop3_b32 v12, v45, v12, 4 bitop3:0x36
	v_mov_b32_e32 v17, v16
	v_lshlrev_b32_e32 v173, 4, v14
	v_lshlrev_b32_e32 v179, 4, v12
	v_or_b32_e32 v12, v160, v13
	v_mov_b32_e32 v14, v16
	v_mov_b64_e32 v[68:69], v[16:17]
	v_mov_b64_e32 v[72:73], v[16:17]
	v_mov_b64_e32 v[56:57], v[16:17]
	v_mov_b64_e32 v[52:53], v[16:17]
	v_mov_b64_e32 v[40:41], v[16:17]
	v_mov_b64_e32 v[36:37], v[16:17]
	v_mov_b64_e32 v[28:29], v[16:17]
	v_mov_b64_e32 v[24:25], v[16:17]
	v_mov_b64_e32 v[80:81], v[16:17]
	v_mov_b64_e32 v[76:77], v[16:17]
	v_mov_b64_e32 v[64:65], v[16:17]
	v_mov_b64_e32 v[60:61], v[16:17]
	v_mov_b64_e32 v[48:49], v[16:17]
	v_mov_b64_e32 v[44:45], v[16:17]
	v_mov_b64_e32 v[32:33], v[16:17]
	v_mul_u32_u24_e32 v180, 0x120, v12
	v_mov_b64_e32 v[66:67], v[14:15]
	v_mov_b64_e32 v[70:71], v[14:15]
	v_mov_b64_e32 v[54:55], v[14:15]
	v_mov_b64_e32 v[50:51], v[14:15]
	v_mov_b64_e32 v[38:39], v[14:15]
	v_mov_b64_e32 v[34:35], v[14:15]
	v_mov_b64_e32 v[26:27], v[14:15]
	v_mov_b64_e32 v[22:23], v[14:15]
	v_mov_b64_e32 v[78:79], v[14:15]
	v_mov_b64_e32 v[74:75], v[14:15]
	v_mov_b64_e32 v[62:63], v[14:15]
	v_mov_b64_e32 v[58:59], v[14:15]
	v_mov_b64_e32 v[46:47], v[14:15]
	v_mov_b64_e32 v[42:43], v[14:15]
	v_mov_b64_e32 v[30:31], v[14:15]
	v_mov_b64_e32 v[12:13], v[14:15]
	v_mov_b64_e32 v[14:15], v[16:17]
	s_nop 0
	v_add_u32_e32 v197, v178, v179
	v_add_u32_e32 v196, v178, v173
	ds_read_b128 v[220:223], v196
	ds_read_b128 v[224:227], v197
	ds_read_b128 v[228:231], v196 offset:2048
	ds_read_b128 v[232:235], v197 offset:2048
	ds_read_b128 v[236:239], v196 offset:4096
	ds_read_b128 v[240:243], v197 offset:4096
	ds_read_b128 v[244:247], v196 offset:6144
	ds_read_b128 v[248:251], v197 offset:6144

.LBB0_463:
	v_add_f32_e32 v17, 0, v138
	v_add_f32_e32 v17, v139, v17
	v_add_f32_e32 v17, v140, v17
	v_add_f32_e32 v17, v141, v17
	v_add_f32_e32 v17, v130, v17
	v_add_f32_e32 v17, v131, v17
	v_add_f32_e32 v17, v132, v17
	v_add_f32_e32 v17, v133, v17
	v_add_f32_e32 v17, v122, v17
	v_add_f32_e32 v17, v123, v17
	v_add_f32_e32 v17, v124, v17
	v_add_f32_e32 v17, v125, v17
	v_add_f32_e32 v17, v114, v17
	v_add_f32_e32 v17, v115, v17
	v_add_f32_e32 v17, v116, v17
	v_add_f32_e32 v17, v117, v17
	v_cndmask_b32_e64 v98, v158, 1.0, s[10:11]
	v_fmac_f32_e32 v17, v216, v98
	v_add_f32_e32 v98, 0, v142
	v_add_f32_e32 v98, v143, v98
	v_add_f32_e32 v98, v144, v98
	v_add_f32_e32 v98, v145, v98
	v_add_f32_e32 v98, v134, v98
	v_add_f32_e32 v98, v135, v98
	v_add_f32_e32 v98, v136, v98
	v_add_f32_e32 v98, v137, v98
	v_add_f32_e32 v98, v126, v98
	v_add_f32_e32 v98, v127, v98
	v_add_f32_e32 v98, v128, v98
	v_add_f32_e32 v98, v129, v98
	v_add_f32_e32 v98, v118, v98
	v_add_f32_e32 v98, v119, v98
	v_add_f32_e32 v98, v120, v98
	v_add_f32_e32 v98, v121, v98
	v_cndmask_b32_e64 v99, v156, 1.0, s[8:9]
	v_fmac_f32_e32 v98, v215, v99
	s_cmp_lg_u32 s29, s31
	s_cbranch_scc0 .LBB0_465
	v_mov_b32_e32 v155, v218
	v_mov_b32_e32 v216, v17
	v_mov_b32_e32 v215, v98
	s_mov_b32 s30, s31
	s_branch .LBB0_455
	s_nop 0
